# v41 without barrier-time prefetch of WD and WOUT
# speedup vs baseline: 1.0038x; 1.0017x over previous
.LBB0_170:
	s_mov_b32 m0, s56
	v_lshl_add_u64 v[4:5], v[2:3], 0, s[80:81]
	s_nop 0
	s_add_i32 s80, s80, s75
	s_cmp_lt_u32 s80, 0x1600000
	s_cbranch_scc1 .LBB0_170

.LBB0_1055:
	s_mov_b32 m0, s56
	v_lshl_add_u64 v[4:5], v[2:3], 0, s[80:81]
	s_nop 0
	s_add_i32 s80, s80, s75
	s_cmp_lt_u32 s80, 0x800000
	s_cbranch_scc1 .LBB0_1055
